# v99 + last-layer dead work removed: context query blocks of layer 3's attention skipped (their rows are never read again) and no grid barrier after the final step
# speedup vs baseline: 1.0033x; 1.0031x over previous
; template <int DQK, int DV, int NAT, int VSHIFT, int COMB> ...
;     ...
;     constexpr int NU = COMB ? NB * 8 * 33 : NUNITS, NBIG = COMB ? 1024 : 2048;
;     for (int ui = vcu; ui < NU; ui += G) {
;         int bx_, qb;
;         if (ui < NBIG) { bx_ = ui >> 5; qb = 1 + (ui & 31); } else { bx_ = ui - NBIG; qb = 0; }
.LBB0_703:
	s_add_i32 s29, s29, s90
	v_readlane_b32 s0, v252, 63
	s_movk_i32 s1, 0x41f
	s_cmp_ge_u32 s0, 30
	s_cselect_b32 s1, 0x3ff, s1
	s_cmp_gt_i32 s29, s1
	s_cbranch_scc1 .LBB0_740

; #define GRID_BAR() do { XcdBarrier xb_; xb_.bar = (unsigned*)p.ws; xb_.x = xb_xcc_id(); xb_.st = (volatile LAS unsigned*)(lds + 131072); xcd_barrier(xb_); } while (0)
; DI void xcd_barrier(const XcdBarrier& b) {
;     asm volatile("s_waitcnt vmcnt(0)" ::: "memory");
;     __syncthreads();
;     if (threadIdx.x == 0) {
;         unsigned* bar = b.bar;
;         __builtin_amdgcn_s_waitcnt(0);
;         unsigned nloc = b.st[0], nx = b.st[1];
;         if (nloc == 0u) { xcd_barrier_complete(bar, b.x, nloc, nx); b.st[0] = nloc; b.st[1] = nx; }
; __global__ void __launch_bounds__(512) fwd_kernel(Params p) {
;     ...
;         if (did) GRID_BAR();
.LBB0_771:
.LBB0_772:
	v_readlane_b32 s2, v252, 63
	s_cmp_eq_u32 s2, 39
	s_cbranch_scc1 .LBB0_315
	s_getreg_b32 s2, hwreg(HW_REG_XCC_ID, 0, 4)
	s_waitcnt vmcnt(0)
	s_waitcnt vmcnt(0) lgkmcnt(0)
	s_barrier
	s_mov_b64 s[0:1], exec
	v_readlane_b32 s4, v252, 1
	v_readlane_b32 s5, v252, 2
	s_and_b64 s[4:5], s[0:1], s[4:5]
	s_mov_b64 exec, s[4:5]
	s_cbranch_execz .LBB0_314
	v_readlane_b32 s4, v252, 48
	s_waitcnt vmcnt(0) expcnt(0) lgkmcnt(0)
	s_and_b32 s2, s2, 15
	v_mov_b32_e32 v0, s4
	ds_read_b32 v3, v0
	v_readlane_b32 s4, v252, 49
	s_waitcnt lgkmcnt(0)
	v_cmp_ne_u32_e32 vcc, 0, v3
	v_mov_b32_e32 v0, s4
	ds_read_b32 v2, v0
	s_cbranch_vccnz .LBB0_788
	s_mov_b32 s10, 1
	s_branch .LBB0_776
